# adaLN epilogue loads bias once per tile; prologue pooling-fold loop issues its 52 loads together (global_ instead of flat_)
# speedup vs baseline: 1.0203x; 1.0004x over previous
.LBB0_766:
	s_add_u32 s10, vcc_lo, 0xfffc0080
	s_addc_u32 s11, vcc_hi, -1
	s_add_i32 s36, 0, 0x10000
	s_cmp_eq_u32 s77, 12
	s_cselect_b32 s13, s59, s11
	s_cselect_b32 s12, s74, s10
	v_add_u32_e32 v152, s36, v3
	s_cselect_b32 s11, s9, s27
	s_cselect_b32 s10, s23, s24
	s_add_i32 s0, 0, 0x14000
	ds_read_b128 v[168:171], v152
	ds_read_b128 v[172:175], v152 offset:1024
	ds_read_b128 v[190:193], v152 offset:2048
	ds_read_b128 v[194:197], v152 offset:3072
	v_add_u32_e32 v152, s0, v3
	ds_read_b128 v[198:201], v152
	ds_read_b128 v[202:205], v152 offset:1024
	ds_read_b128 v[206:209], v152 offset:2048
	ds_read_b128 v[210:213], v152 offset:3072
	v_lshl_add_u64 v[164:165], vcc, 0, v[162:163]
	s_add_i32 m0, s15, 0xc000
	ds_read_b128 v[214:217], v167
	ds_read_b128 v[218:221], v167 offset:1024
	ds_read_b128 v[222:225], v167 offset:2048
	ds_read_b128 v[226:229], v167 offset:3072
	ds_read_b128 v[230:233], v167 offset:4096
	ds_read_b128 v[234:237], v167 offset:5120
	ds_read_b128 v[238:241], v167 offset:6144
	ds_read_b128 v[242:245], v167 offset:7168
	global_load_lds_dwordx4 v[164:165], off
	v_lshl_add_u64 v[164:165], vcc, 0, v[160:161]
	s_add_i32 m0, s15, 0xe000
	s_nop 0
	global_load_lds_dwordx4 v[164:165], off
	s_waitcnt vmcnt(8)
	s_waitcnt lgkmcnt(0)
	s_barrier
	s_setprio 1
	s_waitcnt lgkmcnt(0)
	v_mfma_f32_16x16x32_bf16 v[128:131], v[168:171], v[214:217], v[128:131]
	v_mfma_f32_16x16x32_bf16 v[124:127], v[190:193], v[214:217], v[124:127]
	v_mfma_f32_16x16x32_bf16 v[116:119], v[168:171], v[222:225], v[116:119]
	v_mfma_f32_16x16x32_bf16 v[108:111], v[190:193], v[222:225], v[108:111]
	v_mfma_f32_16x16x32_bf16 v[100:103], v[168:171], v[230:233], v[100:103]
	v_mfma_f32_16x16x32_bf16 v[92:95], v[190:193], v[230:233], v[92:95]
	v_mfma_f32_16x16x32_bf16 v[84:87], v[168:171], v[238:241], v[84:87]
	v_mfma_f32_16x16x32_bf16 v[76:79], v[190:193], v[238:241], v[76:79]
	v_mfma_f32_16x16x32_bf16 v[128:131], v[172:175], v[218:221], v[128:131]
	v_mfma_f32_16x16x32_bf16 v[124:127], v[194:197], v[218:221], v[124:127]
	v_mfma_f32_16x16x32_bf16 v[116:119], v[172:175], v[226:229], v[116:119]
	v_mfma_f32_16x16x32_bf16 v[108:111], v[194:197], v[226:229], v[108:111]
	v_mfma_f32_16x16x32_bf16 v[100:103], v[172:175], v[234:237], v[100:103]
	v_mfma_f32_16x16x32_bf16 v[92:95], v[194:197], v[234:237], v[92:95]
	v_mfma_f32_16x16x32_bf16 v[84:87], v[172:175], v[242:245], v[84:87]
	v_mfma_f32_16x16x32_bf16 v[76:79], v[194:197], v[242:245], v[76:79]
	s_setprio 0
	s_setprio 1
	v_mfma_f32_16x16x32_bf16 v[120:123], v[198:201], v[214:217], v[120:123]
	v_mfma_f32_16x16x32_bf16 v[112:115], v[206:209], v[214:217], v[112:115]
	v_mfma_f32_16x16x32_bf16 v[104:107], v[198:201], v[222:225], v[104:107]
	v_mfma_f32_16x16x32_bf16 v[96:99], v[206:209], v[222:225], v[96:99]
	v_mfma_f32_16x16x32_bf16 v[88:91], v[198:201], v[230:233], v[88:91]
	v_mfma_f32_16x16x32_bf16 v[80:83], v[206:209], v[230:233], v[80:83]
	v_mfma_f32_16x16x32_bf16 v[72:75], v[198:201], v[238:241], v[72:75]
	v_mfma_f32_16x16x32_bf16 v[68:71], v[206:209], v[238:241], v[68:71]
	v_mfma_f32_16x16x32_bf16 v[120:123], v[202:205], v[218:221], v[120:123]
	v_mfma_f32_16x16x32_bf16 v[112:115], v[210:213], v[218:221], v[112:115]
	v_mfma_f32_16x16x32_bf16 v[104:107], v[202:205], v[226:229], v[104:107]
	v_mfma_f32_16x16x32_bf16 v[96:99], v[210:213], v[226:229], v[96:99]
	v_mfma_f32_16x16x32_bf16 v[88:91], v[202:205], v[234:237], v[88:91]
	v_mfma_f32_16x16x32_bf16 v[80:83], v[210:213], v[234:237], v[80:83]
	v_mfma_f32_16x16x32_bf16 v[72:75], v[202:205], v[242:245], v[72:75]
	v_mfma_f32_16x16x32_bf16 v[68:71], v[210:213], v[242:245], v[68:71]
	s_setprio 0
	s_barrier
	s_add_i32 s1, s36, s90
	v_lshl_add_u64 v[164:165], s[10:11], 0, v[0:1]
	s_mov_b32 m0, s1
	ds_read_b128 v[214:217], v167 offset:16384
	ds_read_b128 v[218:221], v167 offset:17408
	ds_read_b128 v[222:225], v167 offset:18432
	ds_read_b128 v[226:229], v167 offset:19456
	ds_read_b128 v[230:233], v167 offset:20480
	ds_read_b128 v[234:237], v167 offset:21504
	ds_read_b128 v[238:241], v167 offset:22528
	ds_read_b128 v[242:245], v167 offset:23552
	global_load_lds_dwordx4 v[164:165], off
	s_add_i32 m0, s1, 0x2000
	s_add_u32 s36, s10, 0x40000
	v_lshl_add_u64 v[246:247], s[10:11], 0, v[132:133]
	s_addc_u32 s37, s11, 0
	s_add_i32 s0, s0, s90
	global_load_lds_dwordx4 v[246:247], off
	v_lshl_add_u64 v[248:249], s[36:37], 0, v[0:1]
	s_mov_b32 m0, s0
	v_lshl_add_u64 v[250:251], s[12:13], 0, v[132:133]
	global_load_lds_dwordx4 v[248:249], off
	v_lshl_add_u64 v[248:249], s[36:37], 0, v[132:133]
	s_add_i32 m0, s0, 0x2000
	s_nop 0
	global_load_lds_dwordx4 v[248:249], off
	v_lshl_add_u64 v[248:249], s[12:13], 0, v[0:1]
	s_mov_b32 m0, s15
	s_nop 0
	global_load_lds_dwordx4 v[248:249], off
	s_mov_b32 m0, s91
	s_nop 0
	global_load_lds_dwordx4 v[250:251], off
	s_waitcnt vmcnt(8)
	s_waitcnt lgkmcnt(0)
	s_barrier
	s_setprio 1
	s_waitcnt lgkmcnt(0)
	v_mfma_f32_16x16x32_bf16 v[64:67], v[168:171], v[214:217], v[64:67]
	v_mfma_f32_16x16x32_bf16 v[60:63], v[190:193], v[214:217], v[60:63]
	v_mfma_f32_16x16x32_bf16 v[52:55], v[168:171], v[222:225], v[52:55]
	v_mfma_f32_16x16x32_bf16 v[44:47], v[190:193], v[222:225], v[44:47]
	v_mfma_f32_16x16x32_bf16 v[36:39], v[168:171], v[230:233], v[36:39]
	v_mfma_f32_16x16x32_bf16 v[28:31], v[190:193], v[230:233], v[28:31]
	v_mfma_f32_16x16x32_bf16 v[20:23], v[168:171], v[238:241], v[20:23]
	v_mfma_f32_16x16x32_bf16 v[12:15], v[190:193], v[238:241], v[12:15]
	v_mfma_f32_16x16x32_bf16 v[64:67], v[172:175], v[218:221], v[64:67]
	v_mfma_f32_16x16x32_bf16 v[60:63], v[194:197], v[218:221], v[60:63]
	v_mfma_f32_16x16x32_bf16 v[52:55], v[172:175], v[226:229], v[52:55]
	v_mfma_f32_16x16x32_bf16 v[44:47], v[194:197], v[226:229], v[44:47]
	v_mfma_f32_16x16x32_bf16 v[36:39], v[172:175], v[234:237], v[36:39]
	v_mfma_f32_16x16x32_bf16 v[28:31], v[194:197], v[234:237], v[28:31]
	v_mfma_f32_16x16x32_bf16 v[20:23], v[172:175], v[242:245], v[20:23]
	v_mfma_f32_16x16x32_bf16 v[12:15], v[194:197], v[242:245], v[12:15]
	s_setprio 0
	s_setprio 1
	v_mfma_f32_16x16x32_bf16 v[56:59], v[198:201], v[214:217], v[56:59]
	v_mfma_f32_16x16x32_bf16 v[48:51], v[206:209], v[214:217], v[48:51]
	v_mfma_f32_16x16x32_bf16 v[40:43], v[198:201], v[222:225], v[40:43]
	v_mfma_f32_16x16x32_bf16 v[32:35], v[206:209], v[222:225], v[32:35]
	v_mfma_f32_16x16x32_bf16 v[24:27], v[198:201], v[230:233], v[24:27]
	v_mfma_f32_16x16x32_bf16 v[16:19], v[206:209], v[230:233], v[16:19]
	v_mfma_f32_16x16x32_bf16 v[8:11], v[198:201], v[238:241], v[8:11]
	v_mfma_f32_16x16x32_bf16 v[4:7], v[206:209], v[238:241], v[4:7]
	v_mfma_f32_16x16x32_bf16 v[56:59], v[202:205], v[218:221], v[56:59]
	v_mfma_f32_16x16x32_bf16 v[48:51], v[210:213], v[218:221], v[48:51]
	v_mfma_f32_16x16x32_bf16 v[40:43], v[202:205], v[226:229], v[40:43]
	v_mfma_f32_16x16x32_bf16 v[32:35], v[210:213], v[226:229], v[32:35]
	v_mfma_f32_16x16x32_bf16 v[24:27], v[202:205], v[234:237], v[24:27]
	v_mfma_f32_16x16x32_bf16 v[16:19], v[210:213], v[234:237], v[16:19]
	v_mfma_f32_16x16x32_bf16 v[8:11], v[202:205], v[242:245], v[8:11]
	v_mfma_f32_16x16x32_bf16 v[4:7], v[210:213], v[242:245], v[4:7]
	s_setprio 0
	s_barrier
	s_add_i32 s0, 0, 0x18000
	v_add_u32_e32 v152, s0, v3
	s_add_i32 s1, 0, 0x1c000
	ds_read_b128 v[168:171], v152
	ds_read_b128 v[172:175], v152 offset:1024
	ds_read_b128 v[190:193], v152 offset:2048
	ds_read_b128 v[194:197], v152 offset:3072
	v_add_u32_e32 v152, s1, v3
	ds_read_b128 v[198:201], v152
	ds_read_b128 v[202:205], v152 offset:1024
	ds_read_b128 v[206:209], v152 offset:2048
	ds_read_b128 v[210:213], v152 offset:3072
	s_add_u32 s12, s12, 0x40000
	s_addc_u32 s13, s13, 0
	s_mov_b32 m0, s31
	v_lshl_add_u64 v[152:153], s[12:13], 0, v[0:1]
	ds_read_b128 v[214:217], v167 offset:32768
	ds_read_b128 v[218:221], v167 offset:33792
	ds_read_b128 v[222:225], v167 offset:34816
	ds_read_b128 v[226:229], v167 offset:35840
	ds_read_b128 v[230:233], v167 offset:36864
	ds_read_b128 v[234:237], v167 offset:37888
	ds_read_b128 v[238:241], v167 offset:38912
	ds_read_b128 v[242:245], v167 offset:39936
	global_load_lds_dwordx4 v[152:153], off
	v_lshl_add_u64 v[152:153], s[12:13], 0, v[132:133]
	s_mov_b32 m0, s22
	s_nop 0
	global_load_lds_dwordx4 v[152:153], off
	s_waitcnt vmcnt(8)
	s_waitcnt lgkmcnt(0)
	s_barrier
	s_setprio 1
	s_waitcnt lgkmcnt(0)
	v_mfma_f32_16x16x32_bf16 v[128:131], v[168:171], v[214:217], v[128:131]
	v_mfma_f32_16x16x32_bf16 v[124:127], v[190:193], v[214:217], v[124:127]
	v_mfma_f32_16x16x32_bf16 v[116:119], v[168:171], v[222:225], v[116:119]
	v_mfma_f32_16x16x32_bf16 v[108:111], v[190:193], v[222:225], v[108:111]
	v_mfma_f32_16x16x32_bf16 v[100:103], v[168:171], v[230:233], v[100:103]
	v_mfma_f32_16x16x32_bf16 v[92:95], v[190:193], v[230:233], v[92:95]
	v_mfma_f32_16x16x32_bf16 v[84:87], v[168:171], v[238:241], v[84:87]
	v_mfma_f32_16x16x32_bf16 v[76:79], v[190:193], v[238:241], v[76:79]
	v_mfma_f32_16x16x32_bf16 v[128:131], v[172:175], v[218:221], v[128:131]
	v_mfma_f32_16x16x32_bf16 v[124:127], v[194:197], v[218:221], v[124:127]
	v_mfma_f32_16x16x32_bf16 v[116:119], v[172:175], v[226:229], v[116:119]
	v_mfma_f32_16x16x32_bf16 v[108:111], v[194:197], v[226:229], v[108:111]
	v_mfma_f32_16x16x32_bf16 v[100:103], v[172:175], v[234:237], v[100:103]
	v_mfma_f32_16x16x32_bf16 v[92:95], v[194:197], v[234:237], v[92:95]
	v_mfma_f32_16x16x32_bf16 v[84:87], v[172:175], v[242:245], v[84:87]
	v_mfma_f32_16x16x32_bf16 v[76:79], v[194:197], v[242:245], v[76:79]
	s_setprio 0
	s_setprio 1
	v_mfma_f32_16x16x32_bf16 v[120:123], v[198:201], v[214:217], v[120:123]
	v_mfma_f32_16x16x32_bf16 v[112:115], v[206:209], v[214:217], v[112:115]
	v_mfma_f32_16x16x32_bf16 v[104:107], v[198:201], v[222:225], v[104:107]
	v_mfma_f32_16x16x32_bf16 v[96:99], v[206:209], v[222:225], v[96:99]
	v_mfma_f32_16x16x32_bf16 v[88:91], v[198:201], v[230:233], v[88:91]
	v_mfma_f32_16x16x32_bf16 v[80:83], v[206:209], v[230:233], v[80:83]
	v_mfma_f32_16x16x32_bf16 v[72:75], v[198:201], v[238:241], v[72:75]
	v_mfma_f32_16x16x32_bf16 v[68:71], v[206:209], v[238:241], v[68:71]
	v_mfma_f32_16x16x32_bf16 v[120:123], v[202:205], v[218:221], v[120:123]
	v_mfma_f32_16x16x32_bf16 v[112:115], v[210:213], v[218:221], v[112:115]
	v_mfma_f32_16x16x32_bf16 v[104:107], v[202:205], v[226:229], v[104:107]
	v_mfma_f32_16x16x32_bf16 v[96:99], v[210:213], v[226:229], v[96:99]
	v_mfma_f32_16x16x32_bf16 v[88:91], v[202:205], v[234:237], v[88:91]
	v_mfma_f32_16x16x32_bf16 v[80:83], v[210:213], v[234:237], v[80:83]
	v_mfma_f32_16x16x32_bf16 v[72:75], v[202:205], v[242:245], v[72:75]
	v_mfma_f32_16x16x32_bf16 v[68:71], v[210:213], v[242:245], v[68:71]
	s_setprio 0
	s_barrier
	s_add_i32 s0, s0, s90
	v_lshl_add_u64 v[152:153], v[164:165], 0, s[84:85]
	s_mov_b32 m0, s0
	ds_read_b128 v[214:217], v167 offset:49152
	ds_read_b128 v[218:221], v167 offset:50176
	ds_read_b128 v[222:225], v167 offset:51200
	ds_read_b128 v[226:229], v167 offset:52224
	ds_read_b128 v[230:233], v167 offset:53248
	ds_read_b128 v[234:237], v167 offset:54272
	ds_read_b128 v[238:241], v167 offset:55296
	ds_read_b128 v[242:245], v167 offset:56320
	global_load_lds_dwordx4 v[152:153], off
	s_add_i32 m0, s0, 0x2000
	s_add_u32 s10, s10, 0x40080
	v_lshl_add_u64 v[152:153], v[246:247], 0, s[84:85]
	s_addc_u32 s11, s11, 0
	s_add_i32 s0, s1, s90
	global_load_lds_dwordx4 v[152:153], off
	v_lshl_add_u64 v[152:153], s[10:11], 0, v[0:1]
	s_mov_b32 m0, s0
	s_nop 0
	global_load_lds_dwordx4 v[152:153], off
	v_lshl_add_u64 v[152:153], s[10:11], 0, v[132:133]
	s_add_i32 m0, s0, 0x2000
	s_nop 0
	global_load_lds_dwordx4 v[152:153], off
	v_lshl_add_u64 v[152:153], v[248:249], 0, s[84:85]
	s_mov_b32 m0, s94
	s_nop 0
	global_load_lds_dwordx4 v[152:153], off
	v_lshl_add_u64 v[152:153], v[250:251], 0, s[84:85]
	s_mov_b32 m0, s70
	s_nop 0
	global_load_lds_dwordx4 v[152:153], off
	s_waitcnt vmcnt(8)
	s_waitcnt lgkmcnt(0)
	s_barrier
	s_setprio 1
	s_waitcnt lgkmcnt(0)
	v_mfma_f32_16x16x32_bf16 v[64:67], v[168:171], v[214:217], v[64:67]
	v_mfma_f32_16x16x32_bf16 v[60:63], v[190:193], v[214:217], v[60:63]
	v_mfma_f32_16x16x32_bf16 v[52:55], v[168:171], v[222:225], v[52:55]
	v_mfma_f32_16x16x32_bf16 v[44:47], v[190:193], v[222:225], v[44:47]
	v_mfma_f32_16x16x32_bf16 v[36:39], v[168:171], v[230:233], v[36:39]
	v_mfma_f32_16x16x32_bf16 v[28:31], v[190:193], v[230:233], v[28:31]
	v_mfma_f32_16x16x32_bf16 v[20:23], v[168:171], v[238:241], v[20:23]
	v_mfma_f32_16x16x32_bf16 v[12:15], v[190:193], v[238:241], v[12:15]
	v_mfma_f32_16x16x32_bf16 v[64:67], v[172:175], v[218:221], v[64:67]
	v_mfma_f32_16x16x32_bf16 v[60:63], v[194:197], v[218:221], v[60:63]
	v_mfma_f32_16x16x32_bf16 v[52:55], v[172:175], v[226:229], v[52:55]
	v_mfma_f32_16x16x32_bf16 v[44:47], v[194:197], v[226:229], v[44:47]
	v_mfma_f32_16x16x32_bf16 v[36:39], v[172:175], v[234:237], v[36:39]
	v_mfma_f32_16x16x32_bf16 v[28:31], v[194:197], v[234:237], v[28:31]
	v_mfma_f32_16x16x32_bf16 v[20:23], v[172:175], v[242:245], v[20:23]
	v_mfma_f32_16x16x32_bf16 v[12:15], v[194:197], v[242:245], v[12:15]
	s_setprio 0
	s_setprio 1
	v_mfma_f32_16x16x32_bf16 v[56:59], v[198:201], v[214:217], v[56:59]
	v_mfma_f32_16x16x32_bf16 v[48:51], v[206:209], v[214:217], v[48:51]
	v_mfma_f32_16x16x32_bf16 v[40:43], v[198:201], v[222:225], v[40:43]
	v_mfma_f32_16x16x32_bf16 v[32:35], v[206:209], v[222:225], v[32:35]
	v_mfma_f32_16x16x32_bf16 v[24:27], v[198:201], v[230:233], v[24:27]
	v_mfma_f32_16x16x32_bf16 v[16:19], v[206:209], v[230:233], v[16:19]
	v_mfma_f32_16x16x32_bf16 v[8:11], v[198:201], v[238:241], v[8:11]
	v_mfma_f32_16x16x32_bf16 v[4:7], v[206:209], v[238:241], v[4:7]
	v_mfma_f32_16x16x32_bf16 v[56:59], v[202:205], v[218:221], v[56:59]
	v_mfma_f32_16x16x32_bf16 v[48:51], v[210:213], v[218:221], v[48:51]
	v_mfma_f32_16x16x32_bf16 v[40:43], v[202:205], v[226:229], v[40:43]
	v_mfma_f32_16x16x32_bf16 v[32:35], v[210:213], v[226:229], v[32:35]
	v_mfma_f32_16x16x32_bf16 v[24:27], v[202:205], v[234:237], v[24:27]
	v_mfma_f32_16x16x32_bf16 v[16:19], v[210:213], v[234:237], v[16:19]
	v_mfma_f32_16x16x32_bf16 v[8:11], v[202:205], v[242:245], v[8:11]
	v_mfma_f32_16x16x32_bf16 v[4:7], v[210:213], v[242:245], v[4:7]
	s_setprio 0
	s_barrier
	s_add_i32 s77, s77, 2
	s_add_u32 s24, s24, 0x100
	s_addc_u32 s27, s27, 0
	s_add_u32 vcc_lo, vcc_lo, 0x100
	s_addc_u32 vcc_hi, vcc_hi, 0
	s_cmp_gt_u32 s77, 13
	s_cbranch_scc0 .LBB0_766
	s_and_b64 vcc, exec, s[6:7]
	s_cbranch_vccz .LBB0_777
	s_barrier
	v_lshl_or_b32 v164, s14, 8, v166
	v_ashrrev_i32_e32 v165, 31, v164
	v_lshlrev_b64 v[190:191], 2, v[164:165]
	v_lshl_add_u64 v[190:191], s[2:3], 0, v[190:191]
	global_load_dwordx4 v[192:195], v[190:191], off
	global_load_dwordx4 v[196:199], v[190:191], off offset:64
	global_load_dwordx4 v[200:203], v[190:191], off offset:512
	global_load_dwordx4 v[204:207], v[190:191], off offset:576
	s_waitcnt vmcnt(0)
	s_and_saveexec_b64 s[10:11], s[38:39]
	s_cbranch_execnz .LBB0_778

.LBB0_770:
	v_lshlrev_b64 v[120:121], 2, v[164:165]
	v_lshl_add_u64 v[120:121], v[136:137], 0, v[120:121]
	v_pk_add_f32 v[114:115], v[118:119], v[194:195]
	v_pk_add_f32 v[112:113], v[116:117], v[192:193]
	flat_store_dwordx4 v[120:121], v[112:115]
	v_pk_add_f32 v[110:111], v[110:111], v[198:199]
	v_pk_add_f32 v[108:109], v[108:109], v[196:197]
	flat_store_dwordx4 v[120:121], v[108:111] offset:64
	v_pk_add_f32 v[106:107], v[106:107], v[202:203]
	v_pk_add_f32 v[104:105], v[104:105], v[200:201]
	flat_store_dwordx4 v[120:121], v[104:107] offset:512
	v_pk_add_f32 v[98:99], v[98:99], v[206:207]
	v_pk_add_f32 v[96:97], v[96:97], v[204:205]
	flat_store_dwordx4 v[120:121], v[96:99] offset:576
	s_or_b64 exec, exec, s[10:11]
	s_and_saveexec_b64 s[10:11], s[42:43]
	s_cbranch_execnz .LBB0_780

.LBB0_772:
	v_lshlrev_b64 v[88:89], 2, v[164:165]
	v_lshl_add_u64 v[88:89], v[140:141], 0, v[88:89]
	v_pk_add_f32 v[82:83], v[86:87], v[194:195]
	v_pk_add_f32 v[80:81], v[84:85], v[192:193]
	flat_store_dwordx4 v[88:89], v[80:83]
	v_pk_add_f32 v[78:79], v[78:79], v[198:199]
	v_pk_add_f32 v[76:77], v[76:77], v[196:197]
	flat_store_dwordx4 v[88:89], v[76:79] offset:64
	v_pk_add_f32 v[74:75], v[74:75], v[202:203]
	v_pk_add_f32 v[72:73], v[72:73], v[200:201]
	flat_store_dwordx4 v[88:89], v[72:75] offset:512
	v_pk_add_f32 v[70:71], v[70:71], v[206:207]
	v_pk_add_f32 v[68:69], v[68:69], v[204:205]
	flat_store_dwordx4 v[88:89], v[68:71] offset:576
	s_or_b64 exec, exec, s[10:11]
	s_and_saveexec_b64 s[10:11], s[46:47]
	s_cbranch_execnz .LBB0_782

.LBB0_774:
	v_lshlrev_b64 v[56:57], 2, v[164:165]
	v_lshl_add_u64 v[56:57], v[144:145], 0, v[56:57]
	v_pk_add_f32 v[50:51], v[54:55], v[194:195]
	v_pk_add_f32 v[48:49], v[52:53], v[192:193]
	flat_store_dwordx4 v[56:57], v[48:51]
	v_pk_add_f32 v[46:47], v[46:47], v[198:199]
	v_pk_add_f32 v[44:45], v[44:45], v[196:197]
	flat_store_dwordx4 v[56:57], v[44:47] offset:64
	v_pk_add_f32 v[42:43], v[42:43], v[202:203]
	v_pk_add_f32 v[40:41], v[40:41], v[200:201]
	flat_store_dwordx4 v[56:57], v[40:43] offset:512
	v_pk_add_f32 v[34:35], v[34:35], v[206:207]
	v_pk_add_f32 v[32:33], v[32:33], v[204:205]
	flat_store_dwordx4 v[56:57], v[32:35] offset:576
	s_or_b64 exec, exec, s[10:11]
	s_and_saveexec_b64 s[10:11], s[50:51]
	s_cbranch_execnz .LBB0_784

.LBB0_776:
	v_lshlrev_b64 v[24:25], 2, v[164:165]
	v_lshl_add_u64 v[24:25], v[158:159], 0, v[24:25]
	v_pk_add_f32 v[18:19], v[22:23], v[194:195]
	v_pk_add_f32 v[16:17], v[20:21], v[192:193]
	flat_store_dwordx4 v[24:25], v[16:19]
	v_pk_add_f32 v[14:15], v[14:15], v[198:199]
	v_pk_add_f32 v[12:13], v[12:13], v[196:197]
	flat_store_dwordx4 v[24:25], v[12:15] offset:64
	v_pk_add_f32 v[10:11], v[10:11], v[202:203]
	v_pk_add_f32 v[8:9], v[8:9], v[200:201]
	flat_store_dwordx4 v[24:25], v[8:11] offset:512
	v_pk_add_f32 v[6:7], v[6:7], v[206:207]
	v_pk_add_f32 v[4:5], v[4:5], v[204:205]
	flat_store_dwordx4 v[24:25], v[4:7] offset:576
	s_or_b64 exec, exec, s[10:11]
	s_andn2_b64 vcc, exec, s[54:55]
	s_mov_b64 s[10:11], -1
	s_cbranch_vccnz .LBB0_762
	s_branch .LBB0_786
.LBB0_777:
	v_lshl_or_b32 v164, s14, 8, v166
	v_ashrrev_i32_e32 v165, 31, v164
	v_lshlrev_b64 v[190:191], 2, v[164:165]
	v_lshl_add_u64 v[190:191], s[2:3], 0, v[190:191]
	global_load_dwordx4 v[192:195], v[190:191], off
	global_load_dwordx4 v[196:199], v[190:191], off offset:64
	global_load_dwordx4 v[200:203], v[190:191], off offset:512
	global_load_dwordx4 v[204:207], v[190:191], off offset:576
	s_waitcnt vmcnt(0)
	s_and_saveexec_b64 s[10:11], s[38:39]
	s_cbranch_execz .LBB0_769
.LBB0_778:
	v_lshlrev_b64 v[152:153], 2, v[164:165]
	v_lshl_add_u64 v[152:153], v[134:135], 0, v[152:153]
	v_pk_add_f32 v[130:131], v[130:131], v[194:195]
	v_pk_add_f32 v[128:129], v[128:129], v[192:193]
	flat_store_dwordx4 v[152:153], v[128:131]
	v_pk_add_f32 v[126:127], v[126:127], v[198:199]
	v_pk_add_f32 v[124:125], v[124:125], v[196:197]
	flat_store_dwordx4 v[152:153], v[124:127] offset:64
	v_pk_add_f32 v[122:123], v[122:123], v[202:203]
	v_pk_add_f32 v[120:121], v[120:121], v[200:201]
	flat_store_dwordx4 v[152:153], v[120:123] offset:512
	v_pk_add_f32 v[114:115], v[114:115], v[206:207]
	v_pk_add_f32 v[112:113], v[112:113], v[204:205]
	flat_store_dwordx4 v[152:153], v[112:115] offset:576
	s_or_b64 exec, exec, s[10:11]
	s_and_saveexec_b64 s[10:11], s[40:41]
	s_cbranch_execnz .LBB0_770

.LBB0_780:
	v_lshlrev_b64 v[104:105], 2, v[164:165]
	v_lshl_add_u64 v[104:105], v[138:139], 0, v[104:105]
	v_pk_add_f32 v[98:99], v[102:103], v[194:195]
	v_pk_add_f32 v[96:97], v[100:101], v[192:193]
	flat_store_dwordx4 v[104:105], v[96:99]
	v_pk_add_f32 v[94:95], v[94:95], v[198:199]
	v_pk_add_f32 v[92:93], v[92:93], v[196:197]
	flat_store_dwordx4 v[104:105], v[92:95] offset:64
	v_pk_add_f32 v[90:91], v[90:91], v[202:203]
	v_pk_add_f32 v[88:89], v[88:89], v[200:201]
	flat_store_dwordx4 v[104:105], v[88:91] offset:512
	v_pk_add_f32 v[82:83], v[82:83], v[206:207]
	v_pk_add_f32 v[80:81], v[80:81], v[204:205]
	flat_store_dwordx4 v[104:105], v[80:83] offset:576
	s_or_b64 exec, exec, s[10:11]
	s_and_saveexec_b64 s[10:11], s[44:45]
	s_cbranch_execnz .LBB0_772

.LBB0_782:
	v_lshlrev_b64 v[72:73], 2, v[164:165]
	v_lshl_add_u64 v[72:73], v[142:143], 0, v[72:73]
	v_pk_add_f32 v[66:67], v[66:67], v[194:195]
	v_pk_add_f32 v[64:65], v[64:65], v[192:193]
	flat_store_dwordx4 v[72:73], v[64:67]
	v_pk_add_f32 v[62:63], v[62:63], v[198:199]
	v_pk_add_f32 v[60:61], v[60:61], v[196:197]
	flat_store_dwordx4 v[72:73], v[60:63] offset:64
	v_pk_add_f32 v[58:59], v[58:59], v[202:203]
	v_pk_add_f32 v[56:57], v[56:57], v[200:201]
	flat_store_dwordx4 v[72:73], v[56:59] offset:512
	v_pk_add_f32 v[50:51], v[50:51], v[206:207]
	v_pk_add_f32 v[48:49], v[48:49], v[204:205]
	flat_store_dwordx4 v[72:73], v[48:51] offset:576
	s_or_b64 exec, exec, s[10:11]
	s_and_saveexec_b64 s[10:11], s[48:49]
	s_cbranch_execnz .LBB0_774

.LBB0_784:
	v_lshlrev_b64 v[40:41], 2, v[164:165]
	v_lshl_add_u64 v[40:41], v[146:147], 0, v[40:41]
	v_pk_add_f32 v[34:35], v[38:39], v[194:195]
	v_pk_add_f32 v[32:33], v[36:37], v[192:193]
	flat_store_dwordx4 v[40:41], v[32:35]
	v_pk_add_f32 v[30:31], v[30:31], v[198:199]
	v_pk_add_f32 v[28:29], v[28:29], v[196:197]
	flat_store_dwordx4 v[40:41], v[28:31] offset:64
	v_pk_add_f32 v[26:27], v[26:27], v[202:203]
	v_pk_add_f32 v[24:25], v[24:25], v[200:201]
	flat_store_dwordx4 v[40:41], v[24:27] offset:512
	v_pk_add_f32 v[18:19], v[18:19], v[206:207]
	v_pk_add_f32 v[16:17], v[16:17], v[204:205]
	flat_store_dwordx4 v[40:41], v[16:19] offset:576
	s_or_b64 exec, exec, s[10:11]
	s_and_saveexec_b64 s[10:11], s[52:53]
	s_cbranch_execnz .LBB0_776

.LBB0_825:
	v_add_co_u32_e32 v4, vcc, 0xffff8000, v0
	s_movk_i32 s12, 0xc000
	s_nop 0
	v_addc_co_u32_e32 v5, vcc, -1, v1, vcc
	global_load_dword v8, v[4:5], off
	v_add_co_u32_e32 v4, vcc, 0xffff9000, v0
	s_nop 1
	v_addc_co_u32_e32 v5, vcc, -1, v1, vcc
	global_load_dword v9, v[4:5], off
	v_add_co_u32_e32 v4, vcc, 0xffffa000, v0
	s_nop 1
	v_addc_co_u32_e32 v5, vcc, -1, v1, vcc
	global_load_dword v10, v[4:5], off
	v_add_co_u32_e32 v4, vcc, 0xffffb000, v0
	s_nop 1
	v_addc_co_u32_e32 v5, vcc, -1, v1, vcc
	global_load_dword v11, v[4:5], off
	v_add_co_u32_e32 v4, vcc, s12, v0
	s_movk_i32 s12, 0x7000
	s_nop 0
	v_addc_co_u32_e32 v5, vcc, -1, v1, vcc
	global_load_dword v48, v[4:5], off
	v_add_co_u32_e32 v4, vcc, 0xffffd000, v0
	s_nop 1
	v_addc_co_u32_e32 v5, vcc, -1, v1, vcc
	global_load_dword v49, v[4:5], off
	v_add_co_u32_e32 v4, vcc, 0xffffe000, v0
	s_nop 1
	v_addc_co_u32_e32 v5, vcc, -1, v1, vcc
	global_load_dword v54, v[4:5], off
	v_add_co_u32_e32 v4, vcc, 0xfffff000, v0
	s_nop 1
	v_addc_co_u32_e32 v5, vcc, -1, v1, vcc
	global_load_dword v55, v[4:5], off
	global_load_dword v36, v[0:1], off
	v_add_co_u32_e32 v4, vcc, s20, v0
	s_nop 1
	v_addc_co_u32_e32 v5, vcc, 0, v1, vcc
	global_load_dword v37, v[4:5], off
	v_add_co_u32_e32 v4, vcc, s95, v0
	s_nop 1
	v_addc_co_u32_e32 v5, vcc, 0, v1, vcc
	global_load_dword v38, v[4:5], off
	v_add_co_u32_e32 v4, vcc, s78, v0
	s_nop 1
	v_addc_co_u32_e32 v5, vcc, 0, v1, vcc
	global_load_dword v39, v[4:5], off
	v_add_co_u32_e32 v4, vcc, s29, v0
	s_nop 1
	v_addc_co_u32_e32 v5, vcc, 0, v1, vcc
	global_load_dword v40, v[4:5], off
	v_add_co_u32_e32 v4, vcc, s76, v0
	s_nop 1
	v_addc_co_u32_e32 v5, vcc, 0, v1, vcc
	global_load_dword v41, v[4:5], off
	v_add_co_u32_e32 v4, vcc, s67, v0
	s_nop 1
	v_addc_co_u32_e32 v5, vcc, 0, v1, vcc
	global_load_dword v42, v[4:5], off
	v_add_co_u32_e32 v4, vcc, s12, v0
	s_add_u32 s12, s9, s2
	s_addc_u32 s13, s10, s3
	v_addc_co_u32_e32 v5, vcc, 0, v1, vcc
	v_mov_b64_e32 v[46:47], s[12:13]
	global_load_dword v43, v[4:5], off
	s_add_u32 s12, s7, s2
	global_load_dwordx4 v[4:7], v[46:47], off
	s_addc_u32 s13, s8, s3
	v_mov_b64_e32 v[44:45], s[12:13]
	s_add_i32 s11, s11, 16
	s_add_u32 s2, s2, 64
	s_addc_u32 s3, s3, 0
	v_lshl_add_u64 v[0:1], v[0:1], 0, s[86:87]
	s_cmp_lt_u32 s11, 48
	global_load_dwordx4 v[96:99], v[44:45], off offset:16
	global_load_dwordx4 v[100:103], v[44:45], off offset:272
	global_load_dwordx4 v[104:107], v[44:45], off offset:528
	global_load_dwordx4 v[108:111], v[44:45], off offset:784
	global_load_dwordx4 v[112:115], v[44:45], off offset:1040
	global_load_dwordx4 v[116:119], v[44:45], off offset:1296
	global_load_dwordx4 v[120:123], v[44:45], off offset:1552
	global_load_dwordx4 v[124:127], v[46:47], off offset:16
	global_load_dwordx4 v[128:131], v[44:45], off
	global_load_dwordx4 v[132:135], v[44:45], off offset:256
	global_load_dwordx4 v[136:139], v[44:45], off offset:512
	global_load_dwordx4 v[140:143], v[44:45], off offset:768
	global_load_dwordx4 v[144:147], v[44:45], off offset:1024
	global_load_dwordx4 v[158:161], v[44:45], off offset:1280
	global_load_dwordx4 v[162:165], v[44:45], off offset:1808
	global_load_dwordx4 v[166:169], v[44:45], off offset:1536
	global_load_dwordx4 v[170:173], v[44:45], off offset:1792
	global_load_dwordx4 v[190:193], v[44:45], off offset:1568
	global_load_dwordx4 v[194:197], v[46:47], off offset:32
	global_load_dwordx4 v[198:201], v[44:45], off offset:1824
	global_load_dwordx4 v[202:205], v[44:45], off offset:1584
	global_load_dwordx4 v[206:209], v[46:47], off offset:48
	global_load_dwordx4 v[210:213], v[44:45], off offset:1840
	global_load_dwordx4 v[214:217], v[44:45], off offset:32
	global_load_dwordx4 v[218:221], v[44:45], off offset:288
	global_load_dwordx4 v[222:225], v[44:45], off offset:48
	global_load_dwordx4 v[226:229], v[44:45], off offset:304
	global_load_dwordx4 v[230:233], v[44:45], off offset:544
	global_load_dwordx4 v[234:237], v[44:45], off offset:800
	global_load_dwordx4 v[238:241], v[44:45], off offset:560
	global_load_dwordx4 v[242:245], v[44:45], off offset:816
	s_waitcnt vmcnt(0) lgkmcnt(0)
	v_mul_f32_e32 v76, v8, v4
	v_mul_f32_e32 v78, v9, v5
	v_mul_f32_e32 v80, v10, v6
	v_mul_f32_e32 v82, v11, v7
	v_mov_b32_e32 v56, v128
	v_mov_b32_e32 v57, v132
	v_pk_fma_f32 v[28:29], v[76:77], v[56:57], v[28:29] op_sel_hi:[0,1,1]
	v_mov_b32_e32 v132, v129
	v_pk_fma_f32 v[28:29], v[78:79], v[132:133], v[28:29] op_sel_hi:[0,1,1]
	v_mov_b32_e32 v128, v130
	v_mov_b32_e32 v129, v134
	v_pk_fma_f32 v[28:29], v[80:81], v[128:129], v[28:29] op_sel_hi:[0,1,1]
	v_mov_b32_e32 v134, v131
	v_pk_mul_f32 v[48:49], v[48:49], v[124:125]
	v_pk_fma_f32 v[28:29], v[82:83], v[134:135], v[28:29] op_sel_hi:[0,1,1]
	v_mov_b32_e32 v128, v96
	v_mov_b32_e32 v129, v100
	v_pk_fma_f32 v[56:57], v[48:49], v[128:129], v[28:29] op_sel_hi:[0,1,1]
	v_mul_f32_e32 v124, v48, v120
	v_pk_mul_f32 v[54:55], v[54:55], v[126:127]
	v_mov_b32_e32 v100, v97
	v_mul_f32_e32 v96, v54, v122
	v_pk_fma_f32 v[100:101], v[48:49], v[100:101], v[56:57] op_sel:[1,0,0]
	v_mov_b32_e32 v28, v136
	v_mov_b32_e32 v29, v140
	v_pk_fma_f32 v[28:29], v[76:77], v[28:29], v[30:31] op_sel_hi:[0,1,1]
	v_mov_b32_e32 v140, v137
	v_pk_fma_f32 v[28:29], v[78:79], v[140:141], v[28:29] op_sel_hi:[0,1,1]
	v_mov_b32_e32 v30, v138
	v_mov_b32_e32 v31, v142
	v_pk_fma_f32 v[28:29], v[80:81], v[30:31], v[28:29] op_sel_hi:[0,1,1]
	v_mov_b32_e32 v142, v139
	v_pk_fma_f32 v[28:29], v[82:83], v[142:143], v[28:29] op_sel_hi:[0,1,1]
	v_mov_b32_e32 v30, v104
	v_mov_b32_e32 v31, v108
	v_pk_fma_f32 v[138:139], v[48:49], v[30:31], v[28:29] op_sel_hi:[0,1,1]
	v_mul_f32_e32 v104, v55, v123
	v_mov_b32_e32 v108, v105
	v_pk_fma_f32 v[108:109], v[48:49], v[108:109], v[138:139] op_sel:[1,0,0]
	v_mov_b32_e32 v136, v144
	v_mov_b32_e32 v137, v158
	v_pk_fma_f32 v[34:35], v[76:77], v[136:137], v[34:35] op_sel_hi:[0,1,1]
	v_mov_b32_e32 v158, v145
	v_pk_fma_f32 v[144:145], v[78:79], v[158:159], v[34:35] op_sel_hi:[0,1,1]
	v_mov_b32_e32 v34, v146
	v_mov_b32_e32 v35, v160
	v_pk_fma_f32 v[144:145], v[80:81], v[34:35], v[144:145] op_sel_hi:[0,1,1]
	v_mov_b32_e32 v160, v147
	v_pk_fma_f32 v[144:145], v[82:83], v[160:161], v[144:145] op_sel_hi:[0,1,1]
	v_mov_b32_e32 v146, v112
	v_mov_b32_e32 v147, v116
	v_pk_fma_f32 v[34:35], v[48:49], v[146:147], v[144:145] op_sel_hi:[0,1,1]
	v_mov_b32_e32 v116, v113
	v_pk_fma_f32 v[116:117], v[48:49], v[116:117], v[34:35] op_sel:[1,0,0]
	v_pk_mul_f32 v[136:137], v[48:49], v[162:163]
	v_mov_b32_e32 v162, v166
	v_mov_b32_e32 v163, v170
	v_pk_fma_f32 v[162:163], v[76:77], v[162:163], v[32:33] op_sel_hi:[0,1,1]
	v_mov_b32_e32 v170, v167
	v_pk_fma_f32 v[162:163], v[78:79], v[170:171], v[162:163] op_sel_hi:[0,1,1]
	v_mov_b32_e32 v32, v168
	v_mov_b32_e32 v33, v172
	v_pk_fma_f32 v[162:163], v[80:81], v[32:33], v[162:163] op_sel_hi:[0,1,1]
	v_mov_b32_e32 v172, v169
	v_pk_fma_f32 v[162:163], v[82:83], v[172:173], v[162:163] op_sel_hi:[0,1,1]
	v_mov_b32_e32 v125, v136
	v_pk_add_f32 v[32:33], v[162:163], v[124:125]
	v_mul_f32_e32 v136, v49, v121
	v_pk_mul_f32 v[112:113], v[54:55], v[164:165]
	v_mov_b32_e32 v97, v112
	v_mov_b32_e32 v105, v113
	v_pk_mul_f32 v[166:167], v[36:37], v[194:195]
	v_pk_mul_f32 v[172:173], v[38:39], v[196:197]
	v_mul_f32_e32 v168, v166, v190
	v_mul_f32_e32 v170, v167, v191
	v_mul_f32_e32 v76, v172, v192
	v_mul_f32_e32 v78, v173, v193
	v_pk_mul_f32 v[198:199], v[166:167], v[198:199]
	v_pk_mul_f32 v[200:201], v[172:173], v[200:201]
	v_mov_b32_e32 v169, v198
	v_mov_b32_e32 v171, v199
	v_mov_b32_e32 v77, v200
	v_mov_b32_e32 v79, v201
	v_pk_mul_f32 v[40:41], v[40:41], v[206:207]
	v_mov_b32_e32 v206, v98
	v_mov_b32_e32 v207, v102
	v_pk_fma_f32 v[100:101], v[54:55], v[206:207], v[100:101] op_sel_hi:[0,1,1]
	v_mov_b32_e32 v102, v99
	v_pk_mul_f32 v[42:43], v[42:43], v[208:209]
	v_pk_fma_f32 v[208:209], v[54:55], v[102:103], v[100:101] op_sel:[1,0,0]
	v_pk_mul_f32 v[46:47], v[40:41], v[210:211]
	v_mul_f32_e32 v202, v40, v202
	v_mul_f32_e32 v210, v41, v203
	v_mov_b32_e32 v203, v46
	v_pk_mul_f32 v[212:213], v[42:43], v[212:213]
	v_mov_b32_e32 v211, v47
	v_mul_f32_e32 v204, v42, v204
	v_mov_b32_e32 v56, v214
	v_mov_b32_e32 v57, v218
	v_pk_fma_f32 v[208:209], v[166:167], v[56:57], v[208:209] op_sel_hi:[0,1,1]
	v_mov_b32_e32 v218, v215
	v_pk_fma_f32 v[214:215], v[166:167], v[218:219], v[208:209] op_sel:[1,0,0]
	v_mov_b32_e32 v218, v216
	v_mov_b32_e32 v219, v220
	v_pk_fma_f32 v[214:215], v[172:173], v[218:219], v[214:215] op_sel_hi:[0,1,1]
	v_mov_b32_e32 v220, v217
	v_pk_fma_f32 v[208:209], v[172:173], v[220:221], v[214:215] op_sel:[1,0,0]
	v_mov_b32_e32 v56, v222
	v_mov_b32_e32 v57, v226
	v_pk_fma_f32 v[208:209], v[40:41], v[56:57], v[208:209] op_sel_hi:[0,1,1]
	v_mov_b32_e32 v226, v223
	v_pk_fma_f32 v[222:223], v[40:41], v[226:227], v[208:209] op_sel:[1,0,0]
	v_mov_b32_e32 v226, v224
	v_mov_b32_e32 v227, v228
	v_pk_fma_f32 v[222:223], v[42:43], v[226:227], v[222:223] op_sel_hi:[0,1,1]
	v_mov_b32_e32 v228, v225
	v_pk_fma_f32 v[228:229], v[42:43], v[228:229], v[222:223] op_sel:[1,0,0]
	v_mov_b32_e32 v222, v106
	v_mov_b32_e32 v223, v110
	v_pk_fma_f32 v[108:109], v[54:55], v[222:223], v[108:109] op_sel_hi:[0,1,1]
	v_mov_b32_e32 v110, v107
	v_pk_fma_f32 v[110:111], v[54:55], v[110:111], v[108:109] op_sel:[1,0,0]
	v_mov_b32_e32 v226, v230
	v_mov_b32_e32 v227, v234
	v_pk_fma_f32 v[110:111], v[166:167], v[226:227], v[110:111] op_sel_hi:[0,1,1]
	v_mov_b32_e32 v234, v231
	v_pk_fma_f32 v[230:231], v[166:167], v[234:235], v[110:111] op_sel:[1,0,0]
	v_mov_b32_e32 v110, v232
	v_mov_b32_e32 v111, v236
	v_pk_fma_f32 v[230:231], v[172:173], v[110:111], v[230:231] op_sel_hi:[0,1,1]
	v_mov_b32_e32 v236, v233
	v_pk_fma_f32 v[110:111], v[172:173], v[236:237], v[230:231] op_sel:[1,0,0]
	v_mov_b32_e32 v226, v238
	v_mov_b32_e32 v227, v242
	v_pk_fma_f32 v[110:111], v[40:41], v[226:227], v[110:111] op_sel_hi:[0,1,1]
	v_mov_b32_e32 v242, v239
	v_pk_fma_f32 v[238:239], v[40:41], v[242:243], v[110:111] op_sel:[1,0,0]
	v_mov_b32_e32 v110, v240
	v_mov_b32_e32 v111, v244
	v_pk_fma_f32 v[238:239], v[42:43], v[110:111], v[238:239] op_sel_hi:[0,1,1]
	v_mov_b32_e32 v244, v241
	v_pk_fma_f32 v[208:209], v[42:43], v[244:245], v[238:239] op_sel:[1,0,0]
	v_mov_b32_e32 v238, v114
	v_mov_b32_e32 v239, v118
	v_pk_fma_f32 v[116:117], v[54:55], v[238:239], v[116:117] op_sel_hi:[0,1,1]
	v_mov_b32_e32 v118, v115
	v_pk_fma_f32 v[118:119], v[54:55], v[118:119], v[116:117] op_sel:[1,0,0]
	global_load_dwordx4 v[100:103], v[44:45], off offset:1056
	global_load_dwordx4 v[120:123], v[44:45], off offset:1312
	global_load_dwordx4 v[124:127], v[44:45], off offset:1072
	global_load_dwordx4 v[128:131], v[44:45], off offset:1328
	s_waitcnt vmcnt(0)
	v_mov_b32_e32 v110, v100
	v_mov_b32_e32 v111, v120
	v_pk_fma_f32 v[118:119], v[166:167], v[110:111], v[118:119] op_sel_hi:[0,1,1]
	v_mov_b32_e32 v120, v101
	v_pk_fma_f32 v[100:101], v[166:167], v[120:121], v[118:119] op_sel:[1,0,0]
	v_mov_b32_e32 v118, v102
	v_mov_b32_e32 v119, v122
	v_pk_fma_f32 v[100:101], v[172:173], v[118:119], v[100:101] op_sel_hi:[0,1,1]
	v_mov_b32_e32 v122, v103
	v_pk_fma_f32 v[118:119], v[172:173], v[122:123], v[100:101] op_sel:[1,0,0]
	v_mov_b32_e32 v110, v124
	v_mov_b32_e32 v111, v128
	v_pk_fma_f32 v[118:119], v[40:41], v[110:111], v[118:119] op_sel_hi:[0,1,1]
	v_mov_b32_e32 v128, v125
	v_pk_fma_f32 v[124:125], v[40:41], v[128:129], v[118:119] op_sel:[1,0,0]
	v_mov_b32_e32 v118, v126
	v_mov_b32_e32 v119, v130
	v_mov_b32_e32 v130, v127
	v_pk_add_f32 v[126:127], v[32:33], v[136:137]
	v_pk_fma_f32 v[124:125], v[42:43], v[118:119], v[124:125] op_sel_hi:[0,1,1]
	v_pk_add_f32 v[126:127], v[126:127], v[96:97]
	v_pk_fma_f32 v[34:35], v[42:43], v[130:131], v[124:125] op_sel:[1,0,0]
	v_pk_add_f32 v[112:113], v[126:127], v[104:105]
	v_mul_f32_e32 v124, v43, v205
	v_pk_add_f32 v[112:113], v[112:113], v[168:169]
	v_mov_b32_e32 v205, v212
	v_pk_add_f32 v[112:113], v[112:113], v[170:171]
	v_mov_b32_e32 v125, v213
	v_pk_add_f32 v[112:113], v[112:113], v[76:77]
	s_nop 0
	v_pk_add_f32 v[112:113], v[112:113], v[78:79]
	s_nop 0
	v_pk_add_f32 v[112:113], v[112:113], v[202:203]
	s_nop 0
	v_pk_add_f32 v[112:113], v[112:113], v[210:211]
	s_nop 0
	v_pk_add_f32 v[112:113], v[112:113], v[204:205]
	s_nop 0
	v_pk_add_f32 v[32:33], v[112:113], v[124:125]
	v_mov_b32_e32 v28, v228
	v_mov_b32_e32 v29, v229
	v_mov_b32_e32 v30, v208
	v_mov_b32_e32 v31, v209
	s_cbranch_scc1 .LBB0_825
	s_lshl_b32 s3, s4, 3
	s_and_b32 s2, s6, 3
	s_and_b32 s3, s3, 0x3c0
	s_lshl_b64 s[0:1], s[0:1], 21
	v_or_b32_e32 v0, s3, v58
	s_add_u32 s0, s62, s0
	s_addc_u32 s1, s63, s1
	v_lshlrev_b32_e32 v0, 11, v0
	v_mov_b32_e32 v1, v2
	v_lshl_add_u64 v[0:1], s[0:1], 0, v[0:1]
	s_lshl_b32 s88, s2, 7
	s_lshl_b32 s0, s4, 4
	v_lshl_add_u64 v[0:1], v[0:1], 0, s[88:89]
	s_and_b32 s88, s0, 0x70
	v_lshl_add_u64 v[0:1], v[0:1], 0, s[88:89]
	v_add_co_u32_e32 v0, vcc, 0x5e00000, v0
	s_add_i32 s4, s4, s68
	s_add_i32 s5, s5, s38
	v_addc_co_u32_e32 v1, vcc, 0, v1, vcc
	s_cmpk_lt_i32 s4, 0x800
	v_cvt_pk_bf16_f32 v4, v28, v29
	v_cvt_pk_bf16_f32 v5, v30, v31
	v_cvt_pk_bf16_f32 v6, v34, v35
	v_cvt_pk_bf16_f32 v7, v32, v33
	global_store_dwordx4 v[0:1], v[4:7], off offset:1024
	s_cbranch_scc1 .LBB0_824
	s_mov_b32 s19, s69
